# filter item loop: static s_setprio 1 for waves 4-7 so one wave's decay epilogue overlaps the other's f32 MFMAs
# speedup vs baseline: 1.0218x; 1.0021x over previous
.LBB0_1319:
	s_waitcnt vmcnt(0)
	v_mov_b32_e32 v42, v179
	s_and_b64 vcc, exec, s[0:1]
	s_cbranch_vccnz .LBB0_1335
	s_movk_i32 s0, 0x800
	v_and_b32_e32 v43, 31, v42
	v_cmp_gt_i32_e64 s[52:53], s0, v42
	v_ashrrev_i32_e32 v0, 2, v42
	s_movk_i32 s0, 0x104
	v_and_b32_e32 v44, -8, v0
	v_and_b32_e32 v0, 0xffffffe0, v42
	v_mad_u32_u24 v45, v43, s0, 32
	s_add_i32 s0, 32, 0x8200
	v_add_u32_e32 v47, s0, v0
	v_readlane_b32 s0, v253, 36
	v_lshlrev_b32_e32 v46, 2, v42
	s_mov_b32 s8, s0
	v_readlane_b32 s1, v253, 37
	v_readfirstlane_b32 s2, v42
	s_cmp_ge_u32 s2, 0x100
	s_cbranch_scc0 .Lp1_np
	s_setprio 1
.Lp1_np:
.LBB0_1321:
	s_cmpk_gt_i32 s8, 0x7ff
	s_cbranch_scc0 .LBB0_1324
	s_add_i32 s0, s8, 0xfffff800
	s_lshr_b32 s10, s0, 4
	v_readlane_b32 s0, v251, 54
	v_readlane_b32 s1, v251, 55
	s_cbranch_execz .LBB0_1325
	s_movk_i32 s9, 0x100
	s_mov_b64 s[4:5], 0x100000
	s_branch .LBB0_1326
